# attention task loop: out-norm gains hoisted, next task id fetched early (on top of the blocked V^T version)
# baseline (speedup 1.0000x reference)
.LBB0_836:
	v_readlane_b32 s35, v253, 32
	s_lshl_b32 s44, s35, 6
	s_waitcnt vmcnt(0)
	v_mov_b32_e32 v2, v179
	s_lshl_b64 s[22:23], s[44:45], 2
	v_readlane_b32 s0, v251, 38
	s_add_u32 s40, s0, s22
	v_readlane_b32 s0, v251, 39
	v_bfe_u32 v1, v2, 4, 2
	v_readlane_b32 s10, v250, 59
	v_readlane_b32 s48, v249, 8
	v_and_b32_e32 v0, 63, v2
	s_addc_u32 s41, s0, s23
	v_and_b32_e32 v32, 15, v2
	v_lshlrev_b32_e32 v34, 3, v1
	v_mov_b32_e32 v35, v157
	v_readlane_b32 s11, v250, 60
	v_readlane_b32 s52, v249, 12
	v_cmp_eq_u32_e64 s[0:1], 0, v0
	v_lshlrev_b32_e32 v36, 2, v1
	v_cmp_eq_u32_e64 s[4:5], 3, v1
	v_cmp_gt_u32_e64 s[6:7], 32, v0
	v_cmp_gt_u32_e64 s[8:9], 16, v0
	v_lshlrev_b32_e32 v156, 6, v32
	v_lshl_add_u64 v[0:1], s[10:11], 0, v[34:35]
	v_readlane_b32 s49, v249, 9
	v_readlane_b32 s50, v249, 10
	v_readlane_b32 s51, v249, 11
	v_readlane_b32 s53, v249, 13
	v_readlane_b32 s56, v249, 16
	v_readlane_b32 s57, v249, 17
	v_readlane_b32 s60, v249, 20
	v_readlane_b32 s61, v249, 21
	s_add_u32 s10, s52, s22
	v_lshl_add_u64 v[38:39], v[0:1], 0, v[156:157]
	v_readlane_b32 s54, v249, 14
	v_readlane_b32 s55, v249, 15
	v_readlane_b32 s62, v249, 22
	s_addc_u32 s11, s53, s23
	v_and_b32_e32 v156, 48, v2
	v_readlane_b32 s60, v253, 17
	v_readlane_b32 s88, v253, 19
	v_readlane_b32 s50, v253, 21
	v_readlane_b32 s48, v253, 23
	v_readlane_b32 s52, v253, 25
	v_readlane_b32 s56, v249, 51
	v_readlane_b32 s70, v253, 37
	v_readlane_b32 s74, v253, 35
	v_readlane_b32 s94, v253, 33
	v_lshl_add_u64 v[40:41], s[10:11], 0, v[156:157]
	v_readlane_b32 s61, v253, 18
	v_readlane_b32 s89, v253, 20
	v_readlane_b32 s51, v253, 22
	v_readlane_b32 s49, v253, 24
	v_readlane_b32 s53, v253, 26
	v_readlane_b32 s57, v249, 52
	v_readlane_b32 s62, v253, 27
	s_mov_b64 s[54:55], 0x1200
	v_readlane_b32 s71, v253, 38
	v_readlane_b32 s75, v253, 36
	v_readlane_b32 s95, v253, 34
	v_readlane_b32 s58, v249, 18
	v_readlane_b32 s59, v249, 19
	v_readlane_b32 s63, v249, 23
	global_load_dwordx4 v[64:67], v[40:41], off
	global_load_dwordx4 v[68:71], v[40:41], off offset:64
	global_load_dwordx4 v[72:75], v[40:41], off offset:128
	global_load_dwordx4 v[76:79], v[40:41], off offset:192
	s_mov_b64 s[10:11], exec
	s_mov_b64 exec, s[0:1]
	v_mov_b32_e32 v81, 1
	global_atomic_add v81, v157, v81, s[40:41] sc0
	s_mov_b64 exec, s[10:11]
	s_branch .LBB0_838

.LBB0_838:
	s_waitcnt vmcnt(0)
	v_readfirstlane_b32 s12, v81
	s_cmpk_gt_i32 s12, 0xfff
	s_mov_b64 s[10:11], -1
	s_cbranch_scc1 .LBB0_837
	s_mov_b64 s[14:15], exec
	s_mov_b64 exec, s[0:1]
	v_mov_b32_e32 v81, 1
	global_atomic_add v81, v157, v81, s[40:41] sc0
	s_mov_b64 exec, s[14:15]
	s_ashr_i32 s14, s12, 9
	s_lshl_b32 s16, s12, 4
	s_and_b32 s11, s16, 0x7f0
	s_ashr_i32 s15, s14, 31
	s_ashr_i32 s10, s12, 7
	s_lshl_b64 s[12:13], s[14:15], 11
	v_or_b32_e32 v33, s11, v32
	v_or_b32_e32 v42, s12, v33
	v_mov_b64_e32 v[0:1], s[20:21]
	s_lshl_b32 s11, s10, 6
	v_mad_u64_u32 v[0:1], s[14:15], v42, s90, v[0:1]
	s_and_b32 s46, s11, 0xc0
	v_mad_i32_i24 v1, s13, v222, v1
	s_lshl_b32 s44, s46, 1
	v_lshl_add_u64 v[0:1], v[0:1], 0, s[44:45]
	v_lshlrev_b32_e32 v156, 1, v34
	v_lshl_add_u64 v[0:1], v[0:1], 0, v[156:157]
	global_load_dwordx4 v[16:19], v[0:1], off
	global_load_dwordx4 v[20:23], v[0:1], off offset:64
	v_and_b32_e32 v0, 63, v217
	v_cmp_gt_u32_e32 vcc, 48, v0
	s_ashr_i32 s11, s10, 31
	s_lshl_b64 s[10:11], s[10:11], 18
	v_cndmask_b32_e64 v1, 0, 16, vcc
	v_cmp_gt_u32_e32 vcc, 16, v0
	v_mov_b32_e32 v28, 0
	v_mov_b32_e32 v43, s13
	v_cndmask_b32_e64 v0, 0, 48, vcc
	v_add_lshl_u32 v50, v0, v217, 2
	v_and_or_b32 v0, v217, 64, v32
	v_mov_b32_e32 v45, s13
	v_or_b32_e32 v44, s12, v32
	v_add_lshl_u32 v35, v1, v217, 2
	v_lshl_or_b32 v37, v217, 2, v223
	v_lshlrev_b32_e32 v51, 2, v0
	v_lshl_add_u64 v[46:47], v[38:39], 0, s[10:11]
	s_and_b32 s58, s16, 0x7e0
	v_mov_b32_e32 v0, 0
	v_mov_b32_e32 v1, v28
	v_mov_b32_e32 v2, v28
	v_mov_b32_e32 v3, v28
	v_mov_b32_e32 v4, 0
	v_mov_b32_e32 v5, v28
	v_mov_b32_e32 v6, v28
	v_mov_b32_e32 v7, v28
	v_mov_b32_e32 v8, 0
	v_mov_b32_e32 v9, v28
	v_mov_b32_e32 v10, v28
	v_mov_b32_e32 v11, v28
	v_mov_b32_e32 v12, 0
	v_mov_b32_e32 v13, v28
	v_mov_b32_e32 v14, v28
	v_mov_b32_e32 v15, v28
.LBB0_844:
	s_mov_b32 s59, s45
	v_lshl_add_u64 v[24:25], v[44:45], 0, s[58:59]
	v_mov_b64_e32 v[26:27], s[20:21]
	v_mad_u64_u32 v[26:27], s[10:11], v24, s90, v[26:27]
	v_mad_i32_i24 v27, v25, s90, v27
	s_lshl_b32 s44, s46, 1
	v_lshl_add_u64 v[24:25], v[26:27], 0, s[44:45]
	v_lshl_add_u64 v[48:49], v[24:25], 0, v[156:157]
	v_add_co_u32_e32 v24, vcc, s76, v48
	s_mov_b64 s[10:11], 0x1e200
	s_nop 0
	v_addc_co_u32_e32 v25, vcc, 0, v49, vcc
	global_load_dwordx4 v[24:27], v[24:25], off offset:512
	v_lshl_add_u64 v[30:31], v[48:49], 0, s[10:11]
	global_load_dwordx4 v[52:55], v[30:31], off offset:64
	global_load_dwordx4 v[58:61], v[48:49], off offset:576
	global_load_dwordx4 v[96:99], v[48:49], off offset:512
	s_lshl_b32 s10, s58, 7
	s_mov_b32 s11, 0
	v_lshl_add_u64 v[116:117], v[46:47], 0, s[10:11]
	global_load_dwordx2 v[100:101], v[116:117], off
	global_load_dwordx2 v[102:103], v[116:117], off offset:32
	global_load_dwordx2 v[104:105], v[116:117], off offset:1024
	global_load_dwordx2 v[106:107], v[116:117], off offset:1056
	global_load_dwordx2 v[108:109], v[116:117], off offset:2048
	global_load_dwordx2 v[110:111], v[116:117], off offset:2080
	global_load_dwordx2 v[112:113], v[116:117], off offset:3072
	global_load_dwordx2 v[114:115], v[116:117], off offset:3104
	v_add_u32_e32 v29, s58, v36
	v_add_u32_e32 v30, 16, v29
	v_cmp_lt_u32_e32 vcc, v30, v33
	s_waitcnt vmcnt(11)
	v_mfma_f32_16x16x32_bf16 v[24:27], v[24:27], v[16:19], 0
	s_waitcnt vmcnt(10)
	v_mfma_f32_16x16x32_bf16 v[24:27], v[52:55], v[20:23], v[24:27]
	s_nop 7
	v_mul_f32_e32 v31, 0x3e000000, v24
	v_max_f32_e32 v30, 0, v31
	v_mul_f32_e64 v31, |v31|, s83
	v_exp_f32_e32 v31, v31
	s_nop 0
	v_add_f32_e32 v31, 1.0, v31
	v_cmp_gt_f32_e64 s[10:11], s93, v31
	s_nop 1
	v_cndmask_b32_e64 v52, 0, 32, s[10:11]
	v_ldexp_f32 v31, v31, v52
	v_log_f32_e32 v31, v31
	s_nop 0
	v_mul_f32_e32 v52, 0x3f317217, v31
	v_fma_f32 v52, v31, s96, -v52
	v_fmac_f32_e32 v52, 0x3377d1cf, v31
	v_fmac_f32_e32 v52, 0x3f317217, v31
	v_cmp_lt_f32_e64 s[12:13], |v31|, s77
	s_nop 1
	v_cndmask_b32_e64 v31, v31, v52, s[12:13]
	v_cndmask_b32_e64 v52, 0, v224, s[10:11]
	v_sub_f32_e32 v31, v31, v52
	v_add_f32_e32 v30, v30, v31
	v_cndmask_b32_e64 v31, 0, -v30, vcc
	v_fma_f32 v24, v24, s97, -v30
	v_mul_f32_e32 v30, 0x3e000000, v25
	v_add_u32_e32 v52, 17, v29
	v_cmp_lt_u32_e64 s[10:11], v52, v33
	v_max_f32_e32 v52, 0, v30
	v_mul_f32_e64 v30, |v30|, s83
	v_exp_f32_e32 v30, v30
	s_nop 0
	v_add_f32_e32 v30, 1.0, v30
	v_cmp_gt_f32_e64 s[12:13], s93, v30
	s_nop 1
	v_cndmask_b32_e64 v53, 0, 32, s[12:13]
	v_ldexp_f32 v30, v30, v53
	v_log_f32_e32 v30, v30
	s_nop 0
	v_mul_f32_e32 v53, 0x3f317217, v30
	v_fma_f32 v53, v30, s96, -v53
	v_fmac_f32_e32 v53, 0x3377d1cf, v30
	v_fmac_f32_e32 v53, 0x3f317217, v30
	v_cmp_lt_f32_e64 s[14:15], |v30|, s77
	s_nop 1
	v_cndmask_b32_e64 v30, v30, v53, s[14:15]
	v_cndmask_b32_e64 v53, 0, v224, s[12:13]
	v_sub_f32_e32 v30, v30, v53
	v_add_f32_e32 v30, v52, v30
	v_cndmask_b32_e64 v52, 0, -v30, s[10:11]
	v_fma_f32 v25, v25, s97, -v30
	v_mul_f32_e32 v30, 0x3e000000, v26
	v_add_u32_e32 v53, 18, v29
	v_cmp_lt_u32_e64 s[12:13], v53, v33
	v_max_f32_e32 v53, 0, v30
	v_mul_f32_e64 v30, |v30|, s83
	v_exp_f32_e32 v30, v30
	s_nop 0
	v_add_f32_e32 v30, 1.0, v30
	v_cmp_gt_f32_e64 s[14:15], s93, v30
	s_nop 1
	v_cndmask_b32_e64 v54, 0, 32, s[14:15]
	v_ldexp_f32 v30, v30, v54
	v_log_f32_e32 v30, v30
	s_nop 0
	v_mul_f32_e32 v54, 0x3f317217, v30
	v_fma_f32 v54, v30, s96, -v54
	v_fmac_f32_e32 v54, 0x3377d1cf, v30
	v_fmac_f32_e32 v54, 0x3f317217, v30
	v_cmp_lt_f32_e64 s[16:17], |v30|, s77
	s_nop 1
	v_cndmask_b32_e64 v30, v30, v54, s[16:17]
	v_cndmask_b32_e64 v54, 0, v224, s[14:15]
	v_sub_f32_e32 v30, v30, v54
	v_add_f32_e32 v30, v53, v30
	v_cndmask_b32_e64 v53, 0, -v30, s[12:13]
	v_fma_f32 v26, v26, s97, -v30
	v_mul_f32_e32 v30, 0x3e000000, v27
	v_add_u32_e32 v54, 19, v29
	v_cmp_lt_u32_e64 s[14:15], v54, v33
	v_max_f32_e32 v54, 0, v30
	v_mul_f32_e64 v30, |v30|, s83
	v_exp_f32_e32 v30, v30
	s_nop 0
	v_add_f32_e32 v30, 1.0, v30
	v_cmp_gt_f32_e64 s[16:17], s93, v30
	s_nop 1
	v_cndmask_b32_e64 v55, 0, 32, s[16:17]
	v_ldexp_f32 v30, v30, v55
	v_log_f32_e32 v30, v30
	s_nop 0
	v_mul_f32_e32 v55, 0x3f317217, v30
	v_fma_f32 v55, v30, s96, -v55
	v_fmac_f32_e32 v55, 0x3377d1cf, v30
	v_fmac_f32_e32 v55, 0x3f317217, v30
	v_cmp_lt_f32_e64 s[18:19], |v30|, s77
	s_nop 1
	v_cndmask_b32_e64 v30, v30, v55, s[18:19]
	v_cndmask_b32_e64 v55, 0, v224, s[16:17]
	v_sub_f32_e32 v30, v30, v55
	v_add_f32_e32 v30, v54, v30
	v_cndmask_b32_e64 v55, 0, -v30, s[14:15]
	v_add_f32_e32 v54, v55, v53
	v_add_f32_e32 v52, v52, v54
	v_fma_f32 v27, v27, s97, -v30
	v_add_f32_e32 v30, v31, v52
	ds_bpermute_b32 v31, v35, v30
	ds_bpermute_b32 v53, v37, v30
	ds_bpermute_b32 v56, v50, v30
	s_waitcnt lgkmcnt(2)
	v_cndmask_b32_e64 v31, v31, 0, s[4:5]
	s_waitcnt lgkmcnt(1)
	v_cndmask_b32_e64 v53, 0, v53, s[6:7]
	v_add_f32_e32 v31, v31, v53
	s_waitcnt lgkmcnt(0)
	v_cndmask_b32_e64 v53, 0, v56, s[8:9]
	v_add_f32_e32 v31, v31, v53
	v_add_f32_e32 v30, v31, v30
	v_add_f32_e32 v31, v28, v31
	v_add_f32_e32 v24, v31, v24
	v_add_f32_e32 v24, v24, v52
	v_mul_f32_e32 v24, 0x3fb8aa3b, v24
	v_exp_f32_e32 v24, v24
	ds_bpermute_b32 v30, v51, v30
	v_cndmask_b32_e32 v53, 0, v24, vcc
	v_add_f32_e32 v24, v31, v25
	v_add_f32_e32 v24, v54, v24
	v_mul_f32_e32 v24, 0x3fb8aa3b, v24
	v_exp_f32_e32 v24, v24
	v_cmp_lt_u32_e32 vcc, v29, v33
	v_cndmask_b32_e64 v54, 0, v24, s[10:11]
	v_add_f32_e32 v24, v31, v26
	v_add_f32_e32 v24, v55, v24
	v_mul_f32_e32 v24, 0x3fb8aa3b, v24
	v_exp_f32_e32 v24, v24
	s_nop 0
	v_cndmask_b32_e64 v55, 0, v24, s[12:13]
	v_add_f32_e32 v24, v31, v27
	v_mul_f32_e32 v24, 0x3fb8aa3b, v24
	v_exp_f32_e32 v24, v24
	s_nop 0
	v_cndmask_b32_e64 v56, 0, v24, s[14:15]
	s_waitcnt vmcnt(8)
	v_mfma_f32_16x16x32_bf16 v[24:27], v[96:99], v[16:19], 0
	v_mfma_f32_16x16x32_bf16 v[24:27], v[58:61], v[20:23], v[24:27]
	s_nop 7
	v_mul_f32_e32 v31, 0x3e000000, v24
	v_max_f32_e32 v48, 0, v31
	v_mul_f32_e64 v31, |v31|, s83
	v_exp_f32_e32 v31, v31
	s_nop 0
	v_add_f32_e32 v31, 1.0, v31
	v_cmp_gt_f32_e64 s[10:11], s93, v31
	s_nop 1
	v_cndmask_b32_e64 v49, 0, 32, s[10:11]
	v_ldexp_f32 v31, v31, v49
	v_log_f32_e32 v31, v31
	s_nop 0
	v_mul_f32_e32 v49, 0x3f317217, v31
	v_fma_f32 v49, v31, s96, -v49
	v_fmac_f32_e32 v49, 0x3377d1cf, v31
	v_fmac_f32_e32 v49, 0x3f317217, v31
	v_cmp_lt_f32_e64 s[12:13], |v31|, s77
	s_nop 1
	v_cndmask_b32_e64 v31, v31, v49, s[12:13]
	v_cndmask_b32_e64 v49, 0, v224, s[10:11]
	v_sub_f32_e32 v31, v31, v49
	v_add_f32_e32 v48, v48, v31
	v_cndmask_b32_e64 v31, 0, -v48, vcc
	v_fma_f32 v24, v24, s97, -v48
	v_mul_f32_e32 v48, 0x3e000000, v25
	v_add_u32_e32 v49, 1, v29
	v_cmp_lt_u32_e64 s[10:11], v49, v33
	v_max_f32_e32 v49, 0, v48
	v_mul_f32_e64 v48, |v48|, s83
	v_exp_f32_e32 v48, v48
	s_nop 0
	v_add_f32_e32 v48, 1.0, v48
	v_cmp_gt_f32_e64 s[12:13], s93, v48
	s_nop 1
	v_cndmask_b32_e64 v52, 0, 32, s[12:13]
	v_ldexp_f32 v48, v48, v52
	v_log_f32_e32 v48, v48
	s_nop 0
	v_mul_f32_e32 v52, 0x3f317217, v48
	v_fma_f32 v52, v48, s96, -v52
	v_fmac_f32_e32 v52, 0x3377d1cf, v48
	v_fmac_f32_e32 v52, 0x3f317217, v48
	v_cmp_lt_f32_e64 s[14:15], |v48|, s77
	s_nop 1
	v_cndmask_b32_e64 v48, v48, v52, s[14:15]
	v_cndmask_b32_e64 v52, 0, v224, s[12:13]
	v_sub_f32_e32 v48, v48, v52
	v_add_f32_e32 v48, v49, v48
	v_cndmask_b32_e64 v49, 0, -v48, s[10:11]
	v_fma_f32 v25, v25, s97, -v48
	v_mul_f32_e32 v48, 0x3e000000, v26
	v_add_u32_e32 v52, 2, v29
	v_cmp_lt_u32_e64 s[12:13], v52, v33
	v_max_f32_e32 v52, 0, v48
	v_mul_f32_e64 v48, |v48|, s83
	v_exp_f32_e32 v48, v48
	v_add_u32_e32 v29, 3, v29
	v_add_f32_e32 v48, 1.0, v48
	v_cmp_gt_f32_e64 s[14:15], s93, v48
	s_nop 1
	v_cndmask_b32_e64 v57, 0, 32, s[14:15]
	v_ldexp_f32 v48, v48, v57
	v_log_f32_e32 v48, v48
	s_nop 0
	v_mul_f32_e32 v57, 0x3f317217, v48
	v_fma_f32 v57, v48, s96, -v57
	v_fmac_f32_e32 v57, 0x3377d1cf, v48
	v_fmac_f32_e32 v57, 0x3f317217, v48
	v_cmp_lt_f32_e64 s[16:17], |v48|, s77
	s_nop 1
	v_cndmask_b32_e64 v48, v48, v57, s[16:17]
	v_cndmask_b32_e64 v57, 0, v224, s[14:15]
	v_sub_f32_e32 v48, v48, v57
	v_add_f32_e32 v48, v52, v48
	v_cndmask_b32_e64 v52, 0, -v48, s[12:13]
	v_fma_f32 v26, v26, s97, -v48
	v_mul_f32_e32 v48, 0x3e000000, v27
	v_cmp_lt_u32_e64 s[14:15], v29, v33
	v_max_f32_e32 v29, 0, v48
	v_mul_f32_e64 v48, |v48|, s83
	v_exp_f32_e32 v48, v48
	s_nop 0
	v_add_f32_e32 v48, 1.0, v48
	v_cmp_gt_f32_e64 s[16:17], s93, v48
	s_nop 1
	v_cndmask_b32_e64 v57, 0, 32, s[16:17]
	v_ldexp_f32 v48, v48, v57
	v_log_f32_e32 v48, v48
	s_nop 0
	v_mul_f32_e32 v57, 0x3f317217, v48
	v_fma_f32 v57, v48, s96, -v57
	v_fmac_f32_e32 v57, 0x3377d1cf, v48
	v_fmac_f32_e32 v57, 0x3f317217, v48
	v_cmp_lt_f32_e64 s[18:19], |v48|, s77
	s_nop 1
	v_cndmask_b32_e64 v48, v48, v57, s[18:19]
	v_cndmask_b32_e64 v57, 0, v224, s[16:17]
	v_sub_f32_e32 v48, v48, v57
	v_add_f32_e32 v29, v29, v48
	v_cndmask_b32_e64 v57, 0, -v29, s[14:15]
	v_add_f32_e32 v58, v57, v52
	v_add_f32_e32 v59, v49, v58
	v_add_f32_e32 v52, v31, v59
	v_fma_f32 v27, v27, s97, -v29
	ds_bpermute_b32 v29, v35, v52
	ds_bpermute_b32 v31, v37, v52
	ds_bpermute_b32 v48, v50, v52
	s_waitcnt lgkmcnt(2)
	v_cndmask_b32_e64 v29, v29, 0, s[4:5]
	s_waitcnt lgkmcnt(1)
	v_cndmask_b32_e64 v31, 0, v31, s[6:7]
	v_add_f32_e32 v29, v29, v31
	s_waitcnt lgkmcnt(0)
	v_cndmask_b32_e64 v31, 0, v48, s[8:9]
	v_pk_add_f32 v[48:49], v[28:29], v[30:31]
	s_nop 0
	v_add_f32_e32 v28, v49, v52
	ds_bpermute_b32 v52, v51, v28
	v_add_f32_e32 v28, v48, v49
	v_add_f32_e32 v24, v28, v24
	v_add_f32_e32 v25, v28, v25
	v_add_f32_e32 v26, v28, v26
	v_add_f32_e32 v24, v24, v59
	v_add_f32_e32 v25, v58, v25
	v_add_f32_e32 v26, v57, v26
	v_add_f32_e32 v27, v28, v27
	v_mul_f32_e32 v24, 0x3fb8aa3b, v24
	v_mul_f32_e32 v25, 0x3fb8aa3b, v25
	v_mul_f32_e32 v26, 0x3fb8aa3b, v26
	v_mul_f32_e32 v27, 0x3fb8aa3b, v27
	v_exp_f32_e32 v24, v24
	v_exp_f32_e32 v25, v25
	v_exp_f32_e32 v26, v26
	v_exp_f32_e32 v27, v27
	v_cndmask_b32_e32 v24, 0, v24, vcc
	v_cndmask_b32_e64 v25, 0, v25, s[10:11]
	v_cndmask_b32_e64 v26, 0, v26, s[12:13]
	v_cndmask_b32_e64 v27, 0, v27, s[14:15]
	v_cvt_pk_bf16_f32 v24, v24, v25
	v_cvt_pk_bf16_f32 v25, v26, v27
	v_cvt_pk_bf16_f32 v26, v53, v54
	v_cvt_pk_bf16_f32 v27, v55, v56
	s_mov_b32 s10, 0xc2b40000
	s_nop 1
	s_waitcnt vmcnt(6)
	v_mfma_f32_16x16x32_bf16 v[12:15], v[100:103], v[24:27], v[12:15]
	s_waitcnt vmcnt(4)
	v_mfma_f32_16x16x32_bf16 v[8:11], v[104:107], v[24:27], v[8:11]
	s_waitcnt vmcnt(2)
	v_mfma_f32_16x16x32_bf16 v[4:7], v[108:111], v[24:27], v[4:7]
	s_waitcnt vmcnt(0)
	v_mfma_f32_16x16x32_bf16 v[0:3], v[112:115], v[24:27], v[0:3]
	s_waitcnt lgkmcnt(0)
	v_add_f32_e32 v28, v48, v52
	v_cmp_gt_f32_e32 vcc, s10, v28
	s_cmp_lg_u64 vcc, exec
	s_cselect_b64 s[10:11], -1, 0
	s_cmp_lg_u32 s58, 0
	s_cselect_b64 s[12:13], -1, 0
	s_and_b64 s[10:11], s[12:13], s[10:11]
	s_sub_i32 s58, s58, 32
	s_and_b64 vcc, exec, s[10:11]
	s_cbranch_vccnz .LBB0_844
	v_pk_mul_f32 v[16:17], v[14:15], v[14:15]
	v_pk_mul_f32 v[18:19], v[12:13], v[12:13]
	v_lshlrev_b32_e32 v156, 1, v36
	v_pk_mov_b32 v[20:21], v[18:19], v[16:17] op_sel:[1,0]
	v_mov_b32_e32 v19, v17
	v_pk_add_f32 v[16:17], v[20:21], v[18:19]
	v_pk_mul_f32 v[18:19], v[10:11], v[10:11]
	v_pk_mul_f32 v[20:21], v[8:9], v[8:9]
	v_pk_add_f32 v[16:17], v[16:17], v[16:17] op_sel:[0,1] op_sel_hi:[1,0]
	v_pk_mov_b32 v[22:23], v[20:21], v[18:19] op_sel:[1,0]
	v_mov_b32_e32 v21, v19
	v_pk_add_f32 v[18:19], v[22:23], v[20:21]
	v_mul_f32_e32 v20, v0, v0
	v_mul_f32_e32 v21, v1, v1
	v_pk_add_f32 v[18:19], v[18:19], v[18:19] op_sel:[0,1] op_sel_hi:[1,0]
	v_mov_b32_e32 v17, v20
	v_mov_b32_e32 v19, v21
	v_pk_add_f32 v[16:17], v[16:17], v[18:19]
	v_mul_f32_e32 v18, v5, v5
	v_mul_f32_e32 v20, v7, v7
	v_mul_f32_e32 v22, v2, v2
	v_mul_f32_e32 v23, v3, v3
	v_pk_fma_f32 v[18:19], v[4:5], v[4:5], v[18:19] op_sel_hi:[1,1,0]
	v_pk_fma_f32 v[20:21], v[6:7], v[6:7], v[20:21] op_sel_hi:[1,1,0]
	v_mov_b32_e32 v19, v22
	v_mov_b32_e32 v21, v23
	v_pk_add_f32 v[18:19], v[18:19], v[20:21]
	v_pk_add_f32 v[16:17], v[16:17], v[18:19]
	v_and_b32_e32 v18, 64, v217
	v_add_f32_e32 v16, v16, v17
	v_xor_b32_e32 v17, 16, v217
	v_add_u32_e32 v18, 64, v18
	v_cmp_lt_i32_e32 vcc, v17, v18
	s_mov_b64 s[10:11], 0
	s_nop 0
	v_cndmask_b32_e32 v17, v217, v17, vcc
	v_lshlrev_b32_e32 v17, 2, v17
	ds_bpermute_b32 v17, v17, v16
	s_waitcnt lgkmcnt(0)
	v_add_f32_e32 v16, v16, v17
	v_xor_b32_e32 v17, 32, v217
	v_cmp_lt_i32_e32 vcc, v17, v18
	s_nop 1
	v_cndmask_b32_e32 v17, v217, v17, vcc
	v_lshlrev_b32_e32 v17, 2, v17
	ds_bpermute_b32 v17, v17, v16
	s_waitcnt lgkmcnt(0)
	v_add_f32_e32 v16, v16, v17
	v_fmamk_f32 v16, v16, 0x3c800000, v212
	v_rsq_f32_e32 v18, v16
	v_lshlrev_b64 v[16:17], 11, v[42:43]
	v_lshl_add_u64 v[16:17], s[36:37], 0, v[16:17]
	v_lshl_add_u64 v[16:17], v[16:17], 0, s[44:45]
	v_pk_mul_f32 v[12:13], v[12:13], v[18:19] op_sel_hi:[1,0]
	v_pk_mul_f32 v[14:15], v[14:15], v[18:19] op_sel_hi:[1,0]
	v_lshl_add_u64 v[16:17], v[16:17], 0, v[156:157]
	v_pk_mul_f32 v[8:9], v[8:9], v[18:19] op_sel_hi:[1,0]
	v_pk_mul_f32 v[10:11], v[10:11], v[18:19] op_sel_hi:[1,0]
	v_pk_mul_f32 v[4:5], v[4:5], v[18:19] op_sel_hi:[1,0]
	v_pk_mul_f32 v[6:7], v[6:7], v[18:19] op_sel_hi:[1,0]
	v_pk_mul_f32 v[0:1], v[0:1], v[18:19] op_sel_hi:[1,0]
	v_pk_mul_f32 v[2:3], v[2:3], v[18:19] op_sel_hi:[1,0]
	v_pk_mul_f32 v[12:13], v[64:65], v[12:13]
	v_pk_mul_f32 v[14:15], v[66:67], v[14:15]
	v_cvt_pk_bf16_f32 v12, v12, v13
	v_cvt_pk_bf16_f32 v13, v14, v15
	global_store_dwordx2 v[16:17], v[12:13], off
	v_pk_mul_f32 v[8:9], v[68:69], v[8:9]
	v_pk_mul_f32 v[10:11], v[70:71], v[10:11]
	v_cvt_pk_bf16_f32 v8, v8, v9
	v_cvt_pk_bf16_f32 v9, v10, v11
	global_store_dwordx2 v[16:17], v[8:9], off offset:32
	v_pk_mul_f32 v[4:5], v[4:5], v[72:73]
	v_pk_mul_f32 v[6:7], v[6:7], v[74:75]
	v_cvt_pk_bf16_f32 v4, v4, v5
	v_cvt_pk_bf16_f32 v5, v6, v7
	global_store_dwordx2 v[16:17], v[4:5], off offset:64
	v_pk_mul_f32 v[0:1], v[0:1], v[76:77]
	v_pk_mul_f32 v[2:3], v[2:3], v[78:79]
	v_cvt_pk_bf16_f32 v0, v0, v1
	v_cvt_pk_bf16_f32 v1, v2, v3
	global_store_dwordx2 v[16:17], v[0:1], off offset:96
	s_branch .LBB0_837
